# prep part 1 split: the 128 workgroups idle in the compression phase convert the first 512 fp8 row items there; the attention-phase copies start one round later
# speedup vs baseline: 1.0037x; 1.0004x over previous
; DI int vb_n() { return (int)gridDim.x * 2; }
; DI void phase_prep(const Params& p, char* smem, int part, int vb) {
;     ...
;   } else {
;     const int NITEMS = 1024 + 1024 + 128 + 128 + 256 + 512 + 32;
;     for (int it0 = vb; it0 < NITEMS; it0 += vb_n()) {
;       int it = it0;
;       if (it < 1024) {
;         int row = it * 16 + wave * 4;
;         fp8_rows<4>(p.pu + (size_t)row * 1024, (unsigned char*)(ws + WS_UBF) + (size_t)row * 1024, (float*)(ws + WS_SU) + row, lane);
;         continue;
.Lcp_done:
.LBB0_350:
	s_cmp_lt_u32 s52, 128
	s_cbranch_scc1 .Lp1c_exit
	s_abs_i32 s1, s88
	v_cvt_f32_u32_e32 v0, s1
	v_readfirstlane_b32 s0, v211
	s_lshr_b32 s0, s0, 8
	s_mul_i32 s0, s0, s54
	v_rcp_iflag_f32_e32 v0, v0
	s_add_i32 s2, s52, s88
	s_sub_i32 s4, 0, s1
	s_add_i32 s0, s2, s0
	v_mul_f32_e32 v0, 0x4f7ffffe, v0
	v_cvt_u32_f32_e32 v0, v0
	s_addk_i32 s0, 0xff80
	s_ashr_i32 s2, s0, 31
	s_abs_i32 s0, s0
	v_readfirstlane_b32 s5, v0
	s_mul_i32 s4, s4, s5
	s_mul_hi_u32 s4, s5, s4
	s_add_i32 s5, s5, s4
	s_mul_hi_u32 s4, s0, s5
	s_mul_i32 s4, s4, s1
	s_sub_i32 s0, s0, s4
	s_sub_i32 s4, s0, s1
	s_cmp_ge_u32 s0, s1
	s_cselect_b32 s0, s4, s0
	s_sub_i32 s4, s0, s1
	s_cmp_ge_u32 s0, s1
	s_cselect_b32 s0, s4, s0
	s_xor_b32 s0, s0, s2
	s_sub_i32 s20, s0, s2
	v_readfirstlane_b32 s0, v211
	s_nop 0
	s_lshr_b32 s0, s0, 8
	s_lshl_b32 s0, s0, 7
	s_add_i32 s20, s52, s0
	s_addk_i32 s20, 0xff80
	s_mov_b32 s3, 0
	v_mov_b32_e32 v0, v210
	s_cmpk_gt_i32 s20, 0x1ff
	s_cbranch_scc1 .Lp1c_exit
	s_add_u32 s6, s86, 0x1180000
	s_addc_u32 s7, s87, 0
	s_add_u32 s21, s86, 0xd00000
	s_addc_u32 s22, s87, 0
	s_add_u32 s23, s86, 0xb00000
	s_addc_u32 s24, s87, 0
	s_add_u32 s25, s86, 0xa00000
	s_addc_u32 s26, s87, 0
	s_add_u32 s27, s86, 0x900000
	s_addc_u32 s28, s87, 0
	v_and_b32_e32 v2, 63, v0
	s_add_u32 s8, s86, 0x2200204
	v_ashrrev_i32_e32 v0, 4, v0
	s_addc_u32 s9, s87, 0
	v_lshlrev_b32_e32 v48, 4, v2
	v_mov_b32_e32 v49, 0
	v_and_b32_e32 v62, -4, v0
	v_lshl_add_u64 v[0:1], s[86:87], 0, v[48:49]
	s_mov_b64 s[4:5], 0x3200200
	s_add_u32 s10, s86, 0x2200200
	s_mov_b64 s[12:13], 0x1200200
	v_cmp_eq_u32_e64 s[0:1], 0, v213
	v_add_u32_e32 v63, 0xffffc000, v62
	v_lshl_add_u64 v[50:51], v[0:1], 0, s[4:5]
	v_cmp_eq_u32_e64 s[4:5], 0, v2
	s_addc_u32 s11, s87, 0
	v_lshl_add_u64 v[52:53], v[0:1], 0, s[12:13]
	v_lshl_add_u64 v[54:55], s[80:81], 0, v[48:49]
	v_lshl_add_u64 v[56:57], s[78:79], 0, v[48:49]
	s_movk_i32 s29, 0x104
	s_movk_i32 s30, 0x7fff
	s_movk_i32 s31, 0x1000
	s_movk_i32 s34, 0x2000
	s_movk_i32 s35, 0x3000
	v_mov_b32_e32 v64, 1
	v_mbcnt_hi_u32_b32 v65, -1, v212
	s_branch .Lp1c_354

; DI int vb_n() { return (int)gridDim.x * 2; }
; DI void phase_prep(const Params& p, char* smem, int part, int vb) {
;     ...
;     for (int it0 = vb; it0 < NITEMS; it0 += vb_n()) {
;       int it = it0;
;       if (it < 1024) {
;         int row = it * 16 + wave * 4;
;         fp8_rows<4>(p.pu + (size_t)row * 1024, (unsigned char*)(ws + WS_UBF) + (size_t)row * 1024, (float*)(ws + WS_SU) + row, lane);
;         continue;
.Lp1c_353:
	s_addk_i32 s20, 0x100
	s_cmpk_lt_i32 s20, 0x200
	s_cbranch_scc0 .Lp1c_exit

; __device__ __forceinline__ unsigned xb_add(unsigned* p, unsigned v) { return __hip_atomic_fetch_add(p, v, __ATOMIC_RELAXED, __HIP_MEMORY_SCOPE_AGENT); }
; __device__ __forceinline__ void xcd_barrier(const XcdBarrier& b) {
;     asm volatile("s_waitcnt vmcnt(0)" ::: "memory");
;     __syncthreads();
;     if (threadIdx.x == 0) {
;         unsigned* bar = b.bar;
;         __builtin_amdgcn_s_waitcnt(0);
;         unsigned nloc = b.st[0], nx = b.st[1];
;         if (nloc == 0u) { xcd_barrier_complete(bar, b.x, nloc, nx); b.st[0] = nloc; b.st[1] = nx; }
;         const unsigned old = xb_add(&bar[XB_XSUB(b.x)], 1u);
;         const unsigned gen = old / nloc;
;         if (old + 1u == (gen + 1u) * nloc) {
; template <int NR>
; DI void fp8_rows(const float* __restrict__ src, unsigned char* __restrict__ dst, float* __restrict__ scale_out, int lane) {
;     ...
;   for (int r = 0; r < NR; ++r) {
;     float amax = 0.f;
; #pragma unroll
;     for (int i = 0; i < 4; ++i)
;       amax = fmaxf(amax, fmaxf(fmaxf(fabsf(v[r][i].x), fabsf(v[r][i].y)), fmaxf(fabsf(v[r][i].z), fabsf(v[r][i].w))));
; #pragma unroll
;     for (int o = 32; o > 0; o >>= 1) amax = fmaxf(amax, __shfl_xor(amax, o));
;     const float scale = amax > 0.f ? amax * (1.f / 440.f) : 1.f;
;     const float inv = 1.f / scale;
;     u32x4 w;
; #pragma unroll
;     for (int i = 0; i < 4; ++i) {
;       int t = 0;
;       t = __builtin_amdgcn_cvt_pk_fp8_f32(v[r][i].x * inv, v[r][i].y * inv, t, false);
;       t = __builtin_amdgcn_cvt_pk_fp8_f32(v[r][i].z * inv, v[r][i].w * inv, t, true);
;       w[i] = (unsigned)t;
;     }
;     *(u32x4*)(dst + (size_t)r * 1024 + lane * 16) = w;
;     if (lane == 0) scale_out[r] = scale;
;   }
.Lp1c_475:
	s_or_b64 exec, exec, s[12:13]
	v_max_f32_e64 v16, |v15|, |v15|
	v_max_f32_e64 v17, |v14|, |v14|
	v_max_f32_e32 v16, v17, v16
	v_max_f32_e64 v17, |v11|, |v11|
	v_max_f32_e64 v18, |v10|, |v10|
	v_max_f32_e32 v17, v18, v17
	v_max3_f32 v16, |v12|, |v13|, v16
	v_max3_f32 v17, |v8|, |v9|, v17
	v_max3_f32 v16, v16, 0, v17
	v_max_f32_e64 v17, |v7|, |v7|
	v_max_f32_e64 v18, |v6|, |v6|
	v_max_f32_e32 v17, v18, v17
	s_waitcnt vmcnt(3)
	v_max_f32_e64 v18, |v3|, |v3|
	v_max_f32_e64 v19, |v2|, |v2|
	v_max_f32_e32 v18, v19, v18
	v_max3_f32 v17, |v4|, |v5|, v17
	v_max3_f32 v18, |v0|, |v1|, v18
	v_max3_f32 v16, v16, v17, v18
	v_mov_b32_e32 v17, v16
	s_nop 1
	v_permlane32_swap_b32_e32 v17, v16
	s_nop 1
	v_mov_b32_e32 v18, 0
	v_mov_b32_e32 v19, 0
	s_waitcnt lgkmcnt(0)
	v_max_f32_e32 v17, v17, v17
	v_max_f32_e32 v16, v16, v17
	v_mov_b32_e32 v17, v16
	s_nop 1
	v_permlane16_swap_b32_e32 v17, v16
	s_nop 1
	s_waitcnt lgkmcnt(0)
	v_max_f32_e32 v17, v17, v17
	v_max_f32_e32 v16, v16, v17
	s_nop 1
	v_mov_b32_dpp v17, v16 row_ror:8 row_mask:0xf bank_mask:0xf
	s_nop 0
	s_waitcnt lgkmcnt(0)
	v_max_f32_e32 v17, v17, v17
	v_max_f32_e32 v16, v16, v17
	s_nop 1
	v_mov_b32_dpp v17, v16 row_ror:4 row_mask:0xf bank_mask:0xf
	s_nop 0
	s_waitcnt lgkmcnt(0)
	v_max_f32_e32 v17, v17, v17
	v_max_f32_e32 v16, v16, v17
	s_nop 1
	v_mov_b32_dpp v17, v16 row_ror:2 row_mask:0xf bank_mask:0xf
	s_nop 0
	s_waitcnt lgkmcnt(0)
	v_max_f32_e32 v17, v17, v17
	v_max_f32_e32 v16, v16, v17
	s_nop 1
	v_mov_b32_dpp v17, v16 row_ror:1 row_mask:0xf bank_mask:0xf
	s_nop 0
	s_waitcnt lgkmcnt(0)
	v_max_f32_e32 v17, v17, v17
	v_max_f32_e32 v16, v16, v17
	v_mul_f32_e32 v17, 0x3b14f209, v16
	v_cmp_lt_f32_e32 vcc, 0, v16
	s_nop 1
	v_cndmask_b32_e32 v16, 1.0, v17, vcc
	v_div_scale_f32 v17, s[12:13], v16, v16, 1.0
	v_rcp_f32_e32 v20, v17
	v_div_scale_f32 v21, vcc, 1.0, v16, 1.0
	v_fma_f32 v22, -v17, v20, 1.0
	v_fmac_f32_e32 v20, v22, v20
	v_mul_f32_e32 v22, v21, v20
	v_fma_f32 v23, -v17, v22, v21
	v_fmac_f32_e32 v22, v23, v20
	v_fma_f32 v17, -v17, v22, v21
	v_div_fmas_f32 v17, v17, v20, v22
	v_div_fixup_f32 v17, v17, v16, 1.0
	v_mul_f32_e32 v12, v12, v17
	v_mul_f32_e32 v13, v13, v17
	v_mul_f32_e32 v8, v8, v17
	v_mul_f32_e32 v9, v9, v17
	v_mul_f32_e32 v4, v4, v17
	v_mul_f32_e32 v5, v5, v17
	v_mov_b32_e32 v20, 0
	v_mul_f32_e32 v0, v0, v17
	v_mul_f32_e32 v1, v1, v17
	v_mov_b32_e32 v21, 0
	v_cvt_pk_fp8_f32 v18, v12, v13
	v_cvt_pk_fp8_f32 v19, v8, v9
	v_cvt_pk_fp8_f32 v20, v4, v5
	v_cvt_pk_fp8_f32 v21, v0, v1
	v_mul_f32_e32 v14, v14, v17
	v_mul_f32_e32 v15, v15, v17
	v_mul_f32_e32 v10, v10, v17
	v_mul_f32_e32 v8, v11, v17
	v_mul_f32_e32 v4, v6, v17
	v_mul_f32_e32 v5, v7, v17
	v_mul_f32_e32 v0, v2, v17
	v_mul_f32_e32 v1, v3, v17
	v_cvt_pk_fp8_f32 v18, v14, v15 op_sel:[0,0,1]
	v_cvt_pk_fp8_f32 v19, v10, v8 op_sel:[0,0,1]
	v_cvt_pk_fp8_f32 v20, v4, v5 op_sel:[0,0,1]
	v_cvt_pk_fp8_f32 v21, v0, v1 op_sel:[0,0,1]
	global_store_dwordx4 v[60:61], v[18:21], off offset:3072
	s_and_saveexec_b64 s[12:13], s[4:5]
	s_cbranch_execz .Lp1c_352
	global_store_dword v[58:59], v16, off offset:24
	s_branch .Lp1c_352
.Lp1c_exit:
.LBB0_477:
	s_waitcnt vmcnt(0)
	s_waitcnt lgkmcnt(0)
	s_barrier
	s_and_saveexec_b64 s[0:1], s[58:59]
	s_cbranch_execz .LBB0_529
	v_mov_b32_e32 v0, 0
	s_waitcnt vmcnt(0) expcnt(0) lgkmcnt(0)
	ds_read_b32 v2, v0 offset:16
	ds_read_b32 v1, v0 offset:20
	s_waitcnt lgkmcnt(1)
	v_cmp_ne_u32_e32 vcc, 0, v2
	s_cbranch_vccnz .LBB0_493
	s_add_u32 s2, s86, 0xec80400
	s_addc_u32 s3, s87, 0
	s_add_u32 s4, s86, 0xec80600
	s_addc_u32 s5, s87, 0
	s_add_u32 s6, s86, 0xec80700
	s_addc_u32 s7, s87, 0
	s_add_u32 s8, s86, 0xec80800
	s_addc_u32 s9, s87, 0
	s_add_u32 s10, s86, 0xec80900
	s_addc_u32 s11, s87, 0
	s_add_u32 s12, s86, 0xec80a00
	s_addc_u32 s13, s87, 0
	s_add_u32 s14, s86, 0xec80b00
	s_addc_u32 s15, s87, 0
	s_add_u32 s16, s86, 0xec80c00
	s_addc_u32 s17, s87, 0
	s_add_u32 s18, s86, 0xec80d00
	s_addc_u32 s19, s87, 0
	s_add_u32 s20, s86, 0xec80e00
	s_addc_u32 s21, s87, 0
	s_add_u32 s22, s86, 0xec80f00
	s_addc_u32 s23, s87, 0
	s_add_u32 s24, s86, 0xec81000
	s_addc_u32 s25, s87, 0
	s_add_u32 s26, s86, 0xec81100
	s_addc_u32 s27, s87, 0
	s_add_u32 s28, s86, 0xec81200
	s_addc_u32 s29, s87, 0
	s_add_u32 s30, s86, 0xec81300
	s_addc_u32 s31, s87, 0
	s_add_u32 s34, s86, 0xec81400
	s_addc_u32 s35, s87, 0
	s_mul_i32 s44, s55, s60
	s_add_u32 s36, s86, 0xec81500
	s_mul_i32 s44, s44, s54
	s_addc_u32 s37, s87, 0
	s_mov_b32 s45, 1
	s_branch .LBB0_481

; DI int vb_id() { return (int)blockIdx.x + half_id() * (int)gridDim.x; }
; DI int vb_n() { return (int)gridDim.x * 2; }
; DI void phase_prep(const Params& p, char* smem, int part, int vb) {
;     ...
;   } else {
;     const int NITEMS = 1024 + 1024 + 128 + 128 + 256 + 512 + 32;
;     for (int it0 = vb; it0 < NITEMS; it0 += vb_n()) {
; __global__ void __launch_bounds__(512) fwd_megakernel(Params p) {
;     ...
;   phase_prep(p, hsm, 1, (vb_id() + vb_n() - 128) % vb_n());
.LBB0_529:
	v_writelane_b32 v253, s58, 32
	s_nop 1
	v_writelane_b32 v253, s59, 33
	v_writelane_b32 v253, s72, 34
	s_nop 1
	v_writelane_b32 v253, s73, 35
	v_writelane_b32 v253, s74, 36
	v_writelane_b32 v253, s75, 37
	v_writelane_b32 v253, s76, 38
	v_writelane_b32 v253, s77, 39
	v_writelane_b32 v253, s78, 40
	v_writelane_b32 v253, s79, 41
	v_writelane_b32 v253, s80, 42
	v_writelane_b32 v253, s81, 43
	v_writelane_b32 v253, s82, 44
	v_writelane_b32 v253, s83, 45
	v_writelane_b32 v253, s84, 46
	v_writelane_b32 v253, s85, 47
	v_writelane_b32 v253, s86, 48
	v_writelane_b32 v253, s87, 49
	s_or_b64 exec, exec, s[0:1]
	v_writelane_b32 v253, s60, 50
	v_writelane_b32 v253, s53, 51
	v_writelane_b32 v253, s56, 52
	v_readfirstlane_b32 s0, v211
	s_lshr_b32 s0, s0, 8
	v_writelane_b32 v253, s57, 53
	v_writelane_b32 v253, s54, 54
	s_mul_i32 s0, s0, s54
	s_add_i32 s94, s0, s52
	v_writelane_b32 v253, s55, 55
	s_cmpk_gt_i32 s94, 0x3ff
	s_waitcnt lgkmcnt(0)
	s_barrier
	v_writelane_b32 v253, s52, 56
	v_lshrrev_b32_e32 v250, 8, v211
	v_mul_u32_u24_e32 v250, 0x13f00, v250
	v_add_u32_e32 v250, 0x13ee0, v250
	v_bfe_u32 v249, v211, 6, 2
	v_lshl_add_u32 v249, v249, 2, v250
	v_mov_b32_e32 v251, 0
	ds_write_b32 v249, v251
	s_waitcnt lgkmcnt(0)
	s_barrier
	v_readfirstlane_b32 s0, v211
	s_nop 0
	s_lshr_b32 s0, s0, 8
	s_cmp_lg_u32 s0, 0
	s_cbranch_scc1 .Lp1a_exit
	v_readlane_b32 s74, v253, 36
	v_readlane_b32 s75, v253, 37
	v_readlane_b32 s76, v253, 38
	v_readlane_b32 s77, v253, 39
	v_readlane_b32 s78, v253, 40
	v_readlane_b32 s79, v253, 41
	v_readlane_b32 s80, v253, 42
	v_readlane_b32 s81, v253, 43
	v_readlane_b32 s86, v253, 48
	v_readlane_b32 s87, v253, 49
	s_nop 3
	s_abs_i32 s1, s88
	v_cvt_f32_u32_e32 v0, s1
	v_readfirstlane_b32 s0, v211
	s_lshr_b32 s0, s0, 8
	s_mul_i32 s0, s0, s54
	v_rcp_iflag_f32_e32 v0, v0
	s_add_i32 s2, s52, s88
	s_sub_i32 s4, 0, s1
	s_add_i32 s0, s2, s0
	v_mul_f32_e32 v0, 0x4f7ffffe, v0
	v_cvt_u32_f32_e32 v0, v0
	s_addk_i32 s0, 0xff80
	s_ashr_i32 s2, s0, 31
	s_abs_i32 s0, s0
	v_readfirstlane_b32 s5, v0
	s_mul_i32 s4, s4, s5
	s_mul_hi_u32 s4, s5, s4
	s_add_i32 s5, s5, s4
	s_mul_hi_u32 s4, s0, s5
	s_mul_i32 s4, s4, s1
	s_sub_i32 s0, s0, s4
	s_sub_i32 s4, s0, s1
	s_cmp_ge_u32 s0, s1
	s_cselect_b32 s0, s4, s0
	s_sub_i32 s4, s0, s1
	s_cmp_ge_u32 s0, s1
	s_cselect_b32 s0, s4, s0
	s_xor_b32 s0, s0, s2
	s_sub_i32 s20, s0, s2
	s_add_i32 s20, s20, s88
	s_mov_b32 s3, 0
	v_mov_b32_e32 v0, v210
	s_cmpk_gt_i32 s20, 0xc1f
	s_cbranch_scc1 .Lp1a_exit
	s_add_u32 s6, s86, 0x1180000
	s_addc_u32 s7, s87, 0
	s_add_u32 s21, s86, 0xd00000
	s_addc_u32 s22, s87, 0
	s_add_u32 s23, s86, 0xb00000
	s_addc_u32 s24, s87, 0
	s_add_u32 s25, s86, 0xa00000
	s_addc_u32 s26, s87, 0
	s_add_u32 s27, s86, 0x900000
	s_addc_u32 s28, s87, 0
	v_and_b32_e32 v2, 63, v0
	s_add_u32 s8, s86, 0x2200204
	v_ashrrev_i32_e32 v0, 4, v0
	s_addc_u32 s9, s87, 0
	v_lshlrev_b32_e32 v48, 4, v2
	v_mov_b32_e32 v49, 0
	v_and_b32_e32 v62, -4, v0
	v_lshl_add_u64 v[0:1], s[86:87], 0, v[48:49]
	s_mov_b64 s[4:5], 0x3200200
	s_add_u32 s10, s86, 0x2200200
	s_mov_b64 s[12:13], 0x1200200
	v_cmp_eq_u32_e64 s[0:1], 0, v213
	v_add_u32_e32 v63, 0xffffc000, v62
	v_lshl_add_u64 v[50:51], v[0:1], 0, s[4:5]
	v_cmp_eq_u32_e64 s[4:5], 0, v2
	s_addc_u32 s11, s87, 0
	v_lshl_add_u64 v[52:53], v[0:1], 0, s[12:13]
	v_lshl_add_u64 v[54:55], s[80:81], 0, v[48:49]
	v_lshl_add_u64 v[56:57], s[78:79], 0, v[48:49]
	s_movk_i32 s29, 0x104
	s_movk_i32 s30, 0x7fff
	s_movk_i32 s31, 0x1000
	s_movk_i32 s34, 0x2000
	s_movk_i32 s35, 0x3000
	v_mov_b32_e32 v64, 1
	v_mbcnt_hi_u32_b32 v65, -1, v212
	s_branch .Lp1a_354

; DI int vb_id() { return (int)blockIdx.x + half_id() * (int)gridDim.x; }
; DI int vb_n() { return (int)gridDim.x * 2; }
; DI void phase_prep(const Params& p, char* smem, int part, int vb) {
;     ...
;   } else {
;     const int NITEMS = 1024 + 1024 + 128 + 128 + 256 + 512 + 32;
;     for (int it0 = vb; it0 < NITEMS; it0 += vb_n()) {
; __global__ void __launch_bounds__(512) fwd_megakernel(Params p) {
;     ...
;   phase_prep(p, hsm, 1, (vb_id() + vb_n() - 128) % vb_n());
.LBB0_752:
	v_readfirstlane_b32 s0, v211
	s_nop 0
	s_lshr_b32 s0, s0, 8
	s_cmp_eq_u32 s0, 0
	s_cbranch_scc1 .Lp1b_exit
	v_readlane_b32 s74, v253, 36
	v_readlane_b32 s75, v253, 37
	v_readlane_b32 s76, v253, 38
	v_readlane_b32 s77, v253, 39
	v_readlane_b32 s78, v253, 40
	v_readlane_b32 s79, v253, 41
	v_readlane_b32 s80, v253, 42
	v_readlane_b32 s81, v253, 43
	v_readlane_b32 s86, v253, 48
	v_readlane_b32 s87, v253, 49
	v_readlane_b32 s52, v253, 56
	v_readlane_b32 s54, v253, 54
	s_nop 3
	s_abs_i32 s1, s88
	v_cvt_f32_u32_e32 v0, s1
	v_readfirstlane_b32 s0, v211
	s_lshr_b32 s0, s0, 8
	s_mul_i32 s0, s0, s54
	v_rcp_iflag_f32_e32 v0, v0
	s_add_i32 s2, s52, s88
	s_sub_i32 s4, 0, s1
	s_add_i32 s0, s2, s0
	v_mul_f32_e32 v0, 0x4f7ffffe, v0
	v_cvt_u32_f32_e32 v0, v0
	s_addk_i32 s0, 0xff80
	s_ashr_i32 s2, s0, 31
	s_abs_i32 s0, s0
	v_readfirstlane_b32 s5, v0
	s_mul_i32 s4, s4, s5
	s_mul_hi_u32 s4, s5, s4
	s_add_i32 s5, s5, s4
	s_mul_hi_u32 s4, s0, s5
	s_mul_i32 s4, s4, s1
	s_sub_i32 s0, s0, s4
	s_sub_i32 s4, s0, s1
	s_cmp_ge_u32 s0, s1
	s_cselect_b32 s0, s4, s0
	s_sub_i32 s4, s0, s1
	s_cmp_ge_u32 s0, s1
	s_cselect_b32 s0, s4, s0
	s_xor_b32 s0, s0, s2
	s_sub_i32 s20, s0, s2
	s_add_i32 s20, s20, s88
	s_mov_b32 s3, 0
	v_mov_b32_e32 v0, v210
	s_cmpk_gt_i32 s20, 0xc1f
	s_cbranch_scc1 .Lp1b_exit
	s_add_u32 s6, s86, 0x1180000
	s_addc_u32 s7, s87, 0
	s_add_u32 s21, s86, 0xd00000
	s_addc_u32 s22, s87, 0
	s_add_u32 s23, s86, 0xb00000
	s_addc_u32 s24, s87, 0
	s_add_u32 s25, s86, 0xa00000
	s_addc_u32 s26, s87, 0
	s_add_u32 s27, s86, 0x900000
	s_addc_u32 s28, s87, 0
	v_and_b32_e32 v2, 63, v0
	s_add_u32 s8, s86, 0x2200204
	v_ashrrev_i32_e32 v0, 4, v0
	s_addc_u32 s9, s87, 0
	v_lshlrev_b32_e32 v48, 4, v2
	v_mov_b32_e32 v49, 0
	v_and_b32_e32 v62, -4, v0
	v_lshl_add_u64 v[0:1], s[86:87], 0, v[48:49]
	s_mov_b64 s[4:5], 0x3200200
	s_add_u32 s10, s86, 0x2200200
	s_mov_b64 s[12:13], 0x1200200
	v_cmp_eq_u32_e64 s[0:1], 0, v213
	v_add_u32_e32 v63, 0xffffc000, v62
	v_lshl_add_u64 v[50:51], v[0:1], 0, s[4:5]
	v_cmp_eq_u32_e64 s[4:5], 0, v2
	s_addc_u32 s11, s87, 0
	v_lshl_add_u64 v[52:53], v[0:1], 0, s[12:13]
	v_lshl_add_u64 v[54:55], s[80:81], 0, v[48:49]
	v_lshl_add_u64 v[56:57], s[78:79], 0, v[48:49]
	s_movk_i32 s29, 0x104
	s_movk_i32 s30, 0x7fff
	s_movk_i32 s31, 0x1000
	s_movk_i32 s34, 0x2000
	s_movk_i32 s35, 0x3000
	v_mov_b32_e32 v64, 1
	v_mbcnt_hi_u32_b32 v65, -1, v212
	s_branch .Lp1b_354
